# P4 S-update: 4-deep pipelined LDS reads for decay/A fragments (both block copies) on top of v52
# baseline (speedup 1.0000x reference)
; #define LAS __attribute__((address_space(3)))
;     ...
;                 for (int kk = 0; kk < 4; ++kk) { const bf16x8_t a = *(const LAS bf16x8_t*)(QA + (16 * tb + fr) * 136 + 32 * kk + 8 * q); const bf16x8_t b = *(const LAS bf16x8_t*)(ST + (16 * w + fr) * 136 + 32 * kk + 8 * q);
;                     oacc[tb] = __builtin_amdgcn_mfma_f32_16x16x32_bf16(a, b, oacc[tb], 0, 0, 0); }
;         }
; #pragma unroll
;         for (int kb = 0; kb < 8; ++kb) { const f32x4 d4 = *(const LAS f32x4*)(DEC + 16 * kb + 4 * q); const bf16x8_t a = *(const LAS bf16x8_t*)(KDT + (16 * kb + fr) * 40 + 8 * q);
;             S[kb] = __builtin_amdgcn_mfma_f32_16x16x32_bf16(a, bV, S[kb] * d4, 0, 0, 0); }
.LBB0_586:
	ds_read_b128 v[108:111], v178
	v_add_u32_e32 v188, v154, v153
	ds_read_b128 v[112:115], v188 offset:37888
	ds_read_b128 v[190:193], v178 offset:64
	ds_read_b128 v[194:197], v188 offset:37952
	v_add_u32_e32 v186, 0, v155
	s_waitcnt lgkmcnt(2)
	v_mfma_f32_16x16x32_bf16 v[108:111], v[108:111], v[112:115], 0
	s_waitcnt lgkmcnt(0)
	v_mfma_f32_16x16x32_bf16 v[108:111], v[190:193], v[194:197], v[108:111]
	ds_read_b128 v[190:193], v178 offset:128
	ds_read_b128 v[204:207], v188 offset:38016
	s_waitcnt lgkmcnt(0)
	v_mfma_f32_16x16x32_bf16 v[108:111], v[190:193], v[204:207], v[108:111]
	ds_read_b128 v[190:193], v178 offset:192
	ds_read_b128 v[208:211], v188 offset:38080
	s_waitcnt lgkmcnt(0)
	v_mfma_f32_16x16x32_bf16 v[108:111], v[190:193], v[208:211], v[108:111]
	ds_read_b128 v[190:193], v178 offset:4352
	ds_read_b128 v[218:221], v178 offset:4416
	ds_read_b128 v[222:225], v178 offset:4480
	ds_read_b128 v[226:229], v178 offset:4544
	s_waitcnt lgkmcnt(3)
	v_mfma_f32_16x16x32_bf16 v[112:115], v[190:193], v[112:115], 0
	s_waitcnt lgkmcnt(2)
	v_mfma_f32_16x16x32_bf16 v[112:115], v[218:221], v[194:197], v[112:115]
	s_waitcnt lgkmcnt(1)
	v_mfma_f32_16x16x32_bf16 v[112:115], v[222:225], v[204:207], v[112:115]
	s_waitcnt lgkmcnt(0)
	v_mfma_f32_16x16x32_bf16 v[112:115], v[226:229], v[208:211], v[112:115]
	v_add_u32_e32 v191, 0x12e00, v186
	v_add_u32_e32 v190, 0x12e40, v186
	v_add_u32_e32 v192, 0x12e80, v186
	v_add_u32_e32 v193, 0x12ec0, v186
	ds_read_b128 v[218:221], v191
	ds_read_b128 v[222:225], v179 offset:17408
	ds_read_b128 v[226:229], v190
	ds_read_b128 v[230:233], v179 offset:18688
	ds_read_b128 v[234:237], v192
	ds_read_b128 v[238:241], v179 offset:19968
	ds_read_b128 v[248:251], v193
	ds_read_b128 v[252:255], v179 offset:21248
	v_add_u32_e32 v194, 0x12f00, v186
	v_add_u32_e32 v195, 0x12f40, v186
	v_add_u32_e32 v196, 0x12f80, v186
	v_add_u32_e32 v197, 0x12fc0, v186
	s_waitcnt lgkmcnt(7)
	v_pk_mul_f32 v[36:37], v[36:37], v[220:221]
	v_pk_mul_f32 v[34:35], v[34:35], v[218:219]
	s_waitcnt lgkmcnt(6)
	s_nop 0
	v_mfma_f32_16x16x32_bf16 v[34:37], v[222:225], v[104:107], v[34:37]
	ds_read_b128 v[218:221], v194
	ds_read_b128 v[222:225], v179 offset:22528
	s_waitcnt lgkmcnt(7)
	v_pk_mul_f32 v[40:41], v[40:41], v[228:229]
	v_pk_mul_f32 v[38:39], v[38:39], v[226:227]
	s_waitcnt lgkmcnt(6)
	s_nop 0
	v_mfma_f32_16x16x32_bf16 v[38:41], v[230:233], v[104:107], v[38:41]
	ds_read_b128 v[226:229], v195
	ds_read_b128 v[230:233], v179 offset:23808
	s_waitcnt lgkmcnt(7)
	v_pk_mul_f32 v[44:45], v[44:45], v[236:237]
	v_pk_mul_f32 v[42:43], v[42:43], v[234:235]
	s_waitcnt lgkmcnt(6)
	s_nop 0
	v_mfma_f32_16x16x32_bf16 v[42:45], v[238:241], v[104:107], v[42:45]
	ds_read_b128 v[234:237], v196
	ds_read_b128 v[238:241], v179 offset:25088
	s_waitcnt lgkmcnt(7)
	v_pk_mul_f32 v[48:49], v[48:49], v[250:251]
	v_pk_mul_f32 v[46:47], v[46:47], v[248:249]
	s_waitcnt lgkmcnt(6)
	s_nop 0
	v_mfma_f32_16x16x32_bf16 v[46:49], v[252:255], v[104:107], v[46:49]
	ds_read_b128 v[204:207], v197
	ds_read_b128 v[208:211], v179 offset:26368
	s_waitcnt lgkmcnt(7)
	v_pk_mul_f32 v[52:53], v[52:53], v[220:221]
	v_pk_mul_f32 v[50:51], v[50:51], v[218:219]
	s_waitcnt lgkmcnt(6)
	s_nop 0
	v_mfma_f32_16x16x32_bf16 v[50:53], v[222:225], v[104:107], v[50:53]
	s_waitcnt lgkmcnt(5)
	v_pk_mul_f32 v[56:57], v[56:57], v[228:229]
	v_pk_mul_f32 v[54:55], v[54:55], v[226:227]
	s_waitcnt lgkmcnt(4)
	s_nop 0
	v_mfma_f32_16x16x32_bf16 v[54:57], v[230:233], v[104:107], v[54:57]
	s_waitcnt lgkmcnt(3)
	v_pk_mul_f32 v[60:61], v[60:61], v[236:237]
	v_pk_mul_f32 v[58:59], v[58:59], v[234:235]
	s_waitcnt lgkmcnt(2)
	s_nop 0
	v_mfma_f32_16x16x32_bf16 v[58:61], v[238:241], v[104:107], v[58:61]
	s_waitcnt lgkmcnt(0)
	s_barrier
; #define LAS __attribute__((address_space(3)))
;     ...
;         for (int kb = 0; kb < 8; ++kb) { const f32x4 d4 = *(const LAS f32x4*)(DEC + 16 * kb + 4 * q); const bf16x8_t a = *(const LAS bf16x8_t*)(KDT + (16 * kb + fr) * 40 + 8 * q);
;             S[kb] = __builtin_amdgcn_mfma_f32_16x16x32_bf16(a, bV, S[kb] * d4, 0, 0, 0); }
;         __syncthreads();
;         if (FULL) {
; #pragma unroll
;             for (int tb = 0; tb < 2; ++tb) { const bf16x8_t a = *(const LAS bf16x8_t*)(Pm + (16 * tb + fr) * 40 + 8 * q); oacc[tb] = __builtin_amdgcn_mfma_f32_16x16x32_bf16(a, bV, oacc[tb], 0, 0, 0); }
;             if (VAR & 1) { asm volatile("" :: "v"(oacc[0]), "v"(oacc[1])); } else {
;             float ssv[8];
; #pragma unroll
;             for (int tb = 0; tb < 2; ++tb)
; #pragma unroll
;                 for (int r = 0; r < 4; ++r) ssv[tb * 4 + r] = dpp_xor_sum16(oacc[tb][r] * oacc[tb][r]);
;             if (fr == 0) {
; #pragma unroll
;                 for (int tb = 0; tb < 2; ++tb)
; #pragma unroll
;                     for (int r = 0; r < 4; ++r) SSQ[(16 * tb + 4 * q + r) * 8 + w] = ssv[tb * 4 + r]; }
	v_pk_mul_f32 v[64:65], v[64:65], v[206:207]
	v_pk_mul_f32 v[62:63], v[62:63], v[204:205]
	ds_read_b128 v[204:207], v180
	s_waitcnt lgkmcnt(0)
	v_mfma_f32_16x16x32_bf16 v[108:111], v[204:207], v[104:107], v[108:111]
	ds_read_b128 v[204:207], v180 offset:1280
	s_nop 6
	v_mul_f32_e32 v189, v111, v111
	v_mfma_f32_16x16x32_bf16 v[62:65], v[208:211], v[104:107], v[62:65]
	s_nop 0
	v_mov_b32_dpp v189, v189 quad_perm:[1,0,3,2] row_mask:0xf bank_mask:0xf bound_ctrl:1
	v_fmac_f32_e32 v189, v111, v111
	v_mul_f32_e32 v186, v110, v110
	s_waitcnt lgkmcnt(0)
	v_mfma_f32_16x16x32_bf16 v[104:107], v[204:207], v[104:107], v[112:115]
	v_add_f32_dpp v189, v189, v189 quad_perm:[2,3,0,1] row_mask:0xf bank_mask:0xf bound_ctrl:1
	v_mov_b32_dpp v186, v186 quad_perm:[1,0,3,2] row_mask:0xf bank_mask:0xf bound_ctrl:1
	s_nop 0
	v_mul_f32_e32 v112, v108, v108
	v_add_f32_dpp v204, v189, v189 row_half_mirror row_mask:0xf bank_mask:0xf bound_ctrl:1
	s_nop 2
	v_mul_f32_e32 v189, v104, v104
	v_mul_f32_e32 v114, v109, v109
	v_mov_b32_dpp v112, v112 quad_perm:[1,0,3,2] row_mask:0xf bank_mask:0xf bound_ctrl:1
	v_mov_b32_dpp v189, v189 quad_perm:[1,0,3,2] row_mask:0xf bank_mask:0xf bound_ctrl:1
	v_fmac_f32_e32 v189, v104, v104
	v_mov_b32_dpp v114, v114 quad_perm:[1,0,3,2] row_mask:0xf bank_mask:0xf bound_ctrl:1
	v_fmac_f32_e32 v112, v108, v108
	v_add_f32_dpp v189, v189, v189 quad_perm:[2,3,0,1] row_mask:0xf bank_mask:0xf bound_ctrl:1
	v_fmac_f32_e32 v114, v109, v109
	v_fmac_f32_e32 v186, v110, v110
	v_add_f32_dpp v206, v189, v189 row_half_mirror row_mask:0xf bank_mask:0xf bound_ctrl:1
	v_mul_f32_e32 v189, v105, v105
	v_add_f32_dpp v112, v112, v112 quad_perm:[2,3,0,1] row_mask:0xf bank_mask:0xf bound_ctrl:1
	v_add_f32_dpp v114, v114, v114 quad_perm:[2,3,0,1] row_mask:0xf bank_mask:0xf bound_ctrl:1
	v_mov_b32_dpp v189, v189 quad_perm:[1,0,3,2] row_mask:0xf bank_mask:0xf bound_ctrl:1
	v_fmac_f32_e32 v189, v105, v105
	v_add_f32_dpp v186, v186, v186 quad_perm:[2,3,0,1] row_mask:0xf bank_mask:0xf bound_ctrl:1
	v_add_f32_dpp v112, v112, v112 row_half_mirror row_mask:0xf bank_mask:0xf bound_ctrl:1
	v_add_f32_dpp v189, v189, v189 quad_perm:[2,3,0,1] row_mask:0xf bank_mask:0xf bound_ctrl:1
	v_add_f32_dpp v114, v114, v114 row_half_mirror row_mask:0xf bank_mask:0xf bound_ctrl:1
	v_add_f32_dpp v186, v186, v186 row_half_mirror row_mask:0xf bank_mask:0xf bound_ctrl:1
	v_add_f32_dpp v208, v189, v189 row_half_mirror row_mask:0xf bank_mask:0xf bound_ctrl:1
	v_mul_f32_e32 v189, v106, v106
	v_mov_b32_dpp v113, v112 row_mirror row_mask:0xf bank_mask:0xf bound_ctrl:1
	v_mov_b32_dpp v115, v114 row_mirror row_mask:0xf bank_mask:0xf bound_ctrl:1
	v_mov_b32_dpp v189, v189 quad_perm:[1,0,3,2] row_mask:0xf bank_mask:0xf bound_ctrl:1
	v_fmac_f32_e32 v189, v106, v106
	v_mov_b32_dpp v203, v186 row_mirror row_mask:0xf bank_mask:0xf bound_ctrl:1
	v_mov_b32_dpp v205, v204 row_mirror row_mask:0xf bank_mask:0xf bound_ctrl:1
	v_add_f32_dpp v189, v189, v189 quad_perm:[2,3,0,1] row_mask:0xf bank_mask:0xf bound_ctrl:1
	v_mov_b32_dpp v207, v206 row_mirror row_mask:0xf bank_mask:0xf bound_ctrl:1
	v_mov_b32_dpp v209, v208 row_mirror row_mask:0xf bank_mask:0xf bound_ctrl:1
	v_add_f32_dpp v210, v189, v189 row_half_mirror row_mask:0xf bank_mask:0xf bound_ctrl:1
	v_mul_f32_e32 v189, v107, v107
	s_nop 0
	v_mov_b32_dpp v211, v210 row_mirror row_mask:0xf bank_mask:0xf bound_ctrl:1
	v_mov_b32_dpp v189, v189 quad_perm:[1,0,3,2] row_mask:0xf bank_mask:0xf bound_ctrl:1
	v_fmac_f32_e32 v189, v107, v107
	s_nop 1
	v_add_f32_dpp v189, v189, v189 quad_perm:[2,3,0,1] row_mask:0xf bank_mask:0xf bound_ctrl:1
	s_nop 1
	v_add_f32_dpp v212, v189, v189 row_half_mirror row_mask:0xf bank_mask:0xf bound_ctrl:1
	v_add_u32_e32 v189, s3, v156
	s_nop 0
	v_mov_b32_dpp v213, v212 row_mirror row_mask:0xf bank_mask:0xf bound_ctrl:1
	s_and_saveexec_b64 vcc, s[10:11]
	s_cbranch_execz .LBB0_588
	v_add_f32_e32 v114, v114, v115
	v_add_f32_e32 v112, v112, v113
	v_add_f32_e32 v212, v212, v213
	v_add_f32_e32 v210, v210, v211
	v_add_f32_e32 v208, v208, v209
	v_add_f32_e32 v206, v206, v207
	v_add_f32_e32 v204, v204, v205
	v_add_f32_e32 v186, v186, v203
	ds_write2_b32 v189, v112, v114 offset1:8
	ds_write2_b32 v189, v186, v204 offset0:16 offset1:24
	ds_write2_b32 v189, v206, v208 offset0:128 offset1:136
	ds_write2_b32 v189, v210, v212 offset0:144 offset1:152

; #define LAS __attribute__((address_space(3)))
;     ...
;                 for (int kk = 0; kk < 4; ++kk) { const bf16x8_t a = *(const LAS bf16x8_t*)(QA + (16 * tb + fr) * 136 + 32 * kk + 8 * q); const bf16x8_t b = *(const LAS bf16x8_t*)(ST + (16 * w + fr) * 136 + 32 * kk + 8 * q);
;                     oacc[tb] = __builtin_amdgcn_mfma_f32_16x16x32_bf16(a, b, oacc[tb], 0, 0, 0); }
;         }
; #pragma unroll
;         for (int kb = 0; kb < 8; ++kb) { const f32x4 d4 = *(const LAS f32x4*)(DEC + 16 * kb + 4 * q); const bf16x8_t a = *(const LAS bf16x8_t*)(KDT + (16 * kb + fr) * 40 + 8 * q);
;             S[kb] = __builtin_amdgcn_mfma_f32_16x16x32_bf16(a, bV, S[kb] * d4, 0, 0, 0); }
.LBB0_631:
	ds_read_b128 v[108:111], v178
	ds_read_b128 v[112:115], v188 offset:37888
	ds_read_b128 v[202:205], v178 offset:64
	ds_read_b128 v[206:209], v188 offset:37952
	s_waitcnt lgkmcnt(2)
	v_mfma_f32_16x16x32_bf16 v[108:111], v[108:111], v[112:115], 0
	s_waitcnt lgkmcnt(0)
	v_mfma_f32_16x16x32_bf16 v[108:111], v[202:205], v[206:209], v[108:111]
	ds_read_b128 v[202:205], v178 offset:128
	ds_read_b128 v[210:213], v188 offset:38016
	s_waitcnt lgkmcnt(0)
	v_mfma_f32_16x16x32_bf16 v[108:111], v[202:205], v[210:213], v[108:111]
	ds_read_b128 v[202:205], v178 offset:192
	ds_read_b128 v[214:217], v188 offset:38080
	s_waitcnt lgkmcnt(0)
	v_mfma_f32_16x16x32_bf16 v[108:111], v[202:205], v[214:217], v[108:111]
	ds_read_b128 v[202:205], v178 offset:4352
	ds_read_b128 v[218:221], v178 offset:4416
	ds_read_b128 v[222:225], v178 offset:4480
	ds_read_b128 v[226:229], v178 offset:4544
	s_waitcnt lgkmcnt(3)
	v_mfma_f32_16x16x32_bf16 v[112:115], v[202:205], v[112:115], 0
	s_waitcnt lgkmcnt(2)
	v_mfma_f32_16x16x32_bf16 v[112:115], v[218:221], v[206:209], v[112:115]
	s_waitcnt lgkmcnt(1)
	v_mfma_f32_16x16x32_bf16 v[112:115], v[222:225], v[210:213], v[112:115]
	s_waitcnt lgkmcnt(0)
	v_mfma_f32_16x16x32_bf16 v[112:115], v[226:229], v[214:217], v[112:115]
	ds_read_b128 v[218:221], v191
	ds_read_b128 v[222:225], v179 offset:17408
	ds_read_b128 v[226:229], v190
	ds_read_b128 v[230:233], v179 offset:18688
	ds_read_b128 v[234:237], v192
	ds_read_b128 v[238:241], v179 offset:19968
	ds_read_b128 v[248:251], v193
	ds_read_b128 v[252:255], v179 offset:21248
	s_waitcnt lgkmcnt(7)
	v_pk_mul_f32 v[36:37], v[36:37], v[220:221]
	v_pk_mul_f32 v[34:35], v[34:35], v[218:219]
	s_waitcnt lgkmcnt(6)
	s_nop 0
	v_mfma_f32_16x16x32_bf16 v[34:37], v[222:225], v[104:107], v[34:37]
	ds_read_b128 v[218:221], v194
	ds_read_b128 v[222:225], v179 offset:22528
	s_waitcnt lgkmcnt(7)
	v_pk_mul_f32 v[40:41], v[40:41], v[228:229]
	v_pk_mul_f32 v[38:39], v[38:39], v[226:227]
	s_waitcnt lgkmcnt(6)
	s_nop 0
	v_mfma_f32_16x16x32_bf16 v[38:41], v[230:233], v[104:107], v[38:41]
	ds_read_b128 v[226:229], v195
	ds_read_b128 v[230:233], v179 offset:23808
	s_waitcnt lgkmcnt(7)
	v_pk_mul_f32 v[44:45], v[44:45], v[236:237]
	v_pk_mul_f32 v[42:43], v[42:43], v[234:235]
	s_waitcnt lgkmcnt(6)
	s_nop 0
	v_mfma_f32_16x16x32_bf16 v[42:45], v[238:241], v[104:107], v[42:45]
	ds_read_b128 v[190:193], v196
	ds_read_b128 v[202:205], v179 offset:25088
	s_waitcnt lgkmcnt(7)
	v_pk_mul_f32 v[48:49], v[48:49], v[250:251]
	v_pk_mul_f32 v[46:47], v[46:47], v[248:249]
	s_waitcnt lgkmcnt(6)
	s_nop 0
	v_mfma_f32_16x16x32_bf16 v[46:49], v[252:255], v[104:107], v[46:49]
	ds_read_b128 v[234:237], v197
	ds_read_b128 v[194:197], v179 offset:26368
	s_waitcnt lgkmcnt(7)
	v_pk_mul_f32 v[52:53], v[52:53], v[220:221]
	v_pk_mul_f32 v[50:51], v[50:51], v[218:219]
	s_waitcnt lgkmcnt(6)
	s_nop 0
	v_mfma_f32_16x16x32_bf16 v[50:53], v[222:225], v[104:107], v[50:53]
	s_waitcnt lgkmcnt(5)
	v_pk_mul_f32 v[56:57], v[56:57], v[228:229]
	v_pk_mul_f32 v[54:55], v[54:55], v[226:227]
	s_waitcnt lgkmcnt(4)
	s_nop 0
	v_mfma_f32_16x16x32_bf16 v[54:57], v[230:233], v[104:107], v[54:57]
	s_waitcnt lgkmcnt(3)
	v_pk_mul_f32 v[60:61], v[60:61], v[192:193]
	v_pk_mul_f32 v[58:59], v[58:59], v[190:191]
	s_waitcnt lgkmcnt(0)
	s_barrier
; #define LAS __attribute__((address_space(3)))
;     ...
;         for (int kb = 0; kb < 8; ++kb) { const f32x4 d4 = *(const LAS f32x4*)(DEC + 16 * kb + 4 * q); const bf16x8_t a = *(const LAS bf16x8_t*)(KDT + (16 * kb + fr) * 40 + 8 * q);
;             S[kb] = __builtin_amdgcn_mfma_f32_16x16x32_bf16(a, bV, S[kb] * d4, 0, 0, 0); }
;         __syncthreads();
;         if (FULL) {
; #pragma unroll
;             for (int tb = 0; tb < 2; ++tb) { const bf16x8_t a = *(const LAS bf16x8_t*)(Pm + (16 * tb + fr) * 40 + 8 * q); oacc[tb] = __builtin_amdgcn_mfma_f32_16x16x32_bf16(a, bV, oacc[tb], 0, 0, 0); }
;             if (VAR & 1) { asm volatile("" :: "v"(oacc[0]), "v"(oacc[1])); } else {
;             float ssv[8];
; #pragma unroll
;             for (int tb = 0; tb < 2; ++tb)
; #pragma unroll
;                 for (int r = 0; r < 4; ++r) ssv[tb * 4 + r] = dpp_xor_sum16(oacc[tb][r] * oacc[tb][r]);
;             if (fr == 0) {
; #pragma unroll
;                 for (int tb = 0; tb < 2; ++tb)
; #pragma unroll
;                     for (int r = 0; r < 4; ++r) SSQ[(16 * tb + 4 * q + r) * 8 + w] = ssv[tb * 4 + r]; }
	v_pk_mul_f32 v[64:65], v[64:65], v[236:237]
	v_pk_mul_f32 v[62:63], v[62:63], v[234:235]
	ds_read_b128 v[190:193], v180
	s_waitcnt lgkmcnt(0)
	v_mfma_f32_16x16x32_bf16 v[108:111], v[190:193], v[104:107], v[108:111]
	ds_read_b128 v[190:193], v180 offset:1280
	s_nop 6
	v_mul_f32_e32 v188, v110, v110
	v_mfma_f32_16x16x32_bf16 v[58:61], v[202:205], v[104:107], v[58:61]
	s_nop 0
	v_mov_b32_dpp v188, v188 quad_perm:[1,0,3,2] row_mask:0xf bank_mask:0xf bound_ctrl:1
	v_fmac_f32_e32 v188, v110, v110
	v_mfma_f32_16x16x32_bf16 v[62:65], v[194:197], v[104:107], v[62:65]
	s_nop 0
	v_add_f32_dpp v188, v188, v188 quad_perm:[2,3,0,1] row_mask:0xf bank_mask:0xf bound_ctrl:1
	s_waitcnt lgkmcnt(0)
	v_mfma_f32_16x16x32_bf16 v[104:107], v[190:193], v[104:107], v[112:115]
	v_mul_f32_e32 v191, v111, v111
	v_add_f32_dpp v188, v188, v188 row_half_mirror row_mask:0xf bank_mask:0xf bound_ctrl:1
	s_nop 0
	v_mul_f32_e32 v112, v108, v108
	v_mul_f32_e32 v114, v109, v109
	s_nop 2
	v_mul_f32_e32 v193, v104, v104
	v_mul_f32_e32 v195, v105, v105
	v_mul_f32_e32 v197, v106, v106
	v_mul_f32_e32 v203, v107, v107
	v_mov_b32_dpp v112, v112 quad_perm:[1,0,3,2] row_mask:0xf bank_mask:0xf bound_ctrl:1
	v_mov_b32_dpp v114, v114 quad_perm:[1,0,3,2] row_mask:0xf bank_mask:0xf bound_ctrl:1
	v_mov_b32_dpp v191, v191 quad_perm:[1,0,3,2] row_mask:0xf bank_mask:0xf bound_ctrl:1
	v_mov_b32_dpp v193, v193 quad_perm:[1,0,3,2] row_mask:0xf bank_mask:0xf bound_ctrl:1
	v_mov_b32_dpp v195, v195 quad_perm:[1,0,3,2] row_mask:0xf bank_mask:0xf bound_ctrl:1
	v_mov_b32_dpp v197, v197 quad_perm:[1,0,3,2] row_mask:0xf bank_mask:0xf bound_ctrl:1
	v_mov_b32_dpp v203, v203 quad_perm:[1,0,3,2] row_mask:0xf bank_mask:0xf bound_ctrl:1
	v_fmac_f32_e32 v112, v108, v108
	v_fmac_f32_e32 v114, v109, v109
	v_fmac_f32_e32 v191, v111, v111
	v_fmac_f32_e32 v193, v104, v104
	v_fmac_f32_e32 v195, v105, v105
	v_fmac_f32_e32 v197, v106, v106
	v_fmac_f32_e32 v203, v107, v107
	v_add_f32_dpp v112, v112, v112 quad_perm:[2,3,0,1] row_mask:0xf bank_mask:0xf bound_ctrl:1
	v_add_f32_dpp v114, v114, v114 quad_perm:[2,3,0,1] row_mask:0xf bank_mask:0xf bound_ctrl:1
	v_add_f32_dpp v191, v191, v191 quad_perm:[2,3,0,1] row_mask:0xf bank_mask:0xf bound_ctrl:1
	v_add_f32_dpp v193, v193, v193 quad_perm:[2,3,0,1] row_mask:0xf bank_mask:0xf bound_ctrl:1
	v_add_f32_dpp v195, v195, v195 quad_perm:[2,3,0,1] row_mask:0xf bank_mask:0xf bound_ctrl:1
	v_add_f32_dpp v197, v197, v197 quad_perm:[2,3,0,1] row_mask:0xf bank_mask:0xf bound_ctrl:1
	v_add_f32_dpp v203, v203, v203 quad_perm:[2,3,0,1] row_mask:0xf bank_mask:0xf bound_ctrl:1
	v_add_f32_dpp v112, v112, v112 row_half_mirror row_mask:0xf bank_mask:0xf bound_ctrl:1
	v_add_f32_dpp v114, v114, v114 row_half_mirror row_mask:0xf bank_mask:0xf bound_ctrl:1
	v_add_f32_dpp v191, v191, v191 row_half_mirror row_mask:0xf bank_mask:0xf bound_ctrl:1
	v_add_f32_dpp v193, v193, v193 row_half_mirror row_mask:0xf bank_mask:0xf bound_ctrl:1
	v_add_f32_dpp v195, v195, v195 row_half_mirror row_mask:0xf bank_mask:0xf bound_ctrl:1
	v_add_f32_dpp v197, v197, v197 row_half_mirror row_mask:0xf bank_mask:0xf bound_ctrl:1
	v_add_f32_dpp v203, v203, v203 row_half_mirror row_mask:0xf bank_mask:0xf bound_ctrl:1
	v_mov_b32_dpp v113, v112 row_mirror row_mask:0xf bank_mask:0xf bound_ctrl:1
	v_mov_b32_dpp v115, v114 row_mirror row_mask:0xf bank_mask:0xf bound_ctrl:1
	v_mov_b32_dpp v190, v188 row_mirror row_mask:0xf bank_mask:0xf bound_ctrl:1
	v_mov_b32_dpp v192, v191 row_mirror row_mask:0xf bank_mask:0xf bound_ctrl:1
	v_mov_b32_dpp v194, v193 row_mirror row_mask:0xf bank_mask:0xf bound_ctrl:1
	v_mov_b32_dpp v196, v195 row_mirror row_mask:0xf bank_mask:0xf bound_ctrl:1
	v_mov_b32_dpp v202, v197 row_mirror row_mask:0xf bank_mask:0xf bound_ctrl:1
	v_mov_b32_dpp v204, v203 row_mirror row_mask:0xf bank_mask:0xf bound_ctrl:1
	s_and_saveexec_b64 s[26:27], s[10:11]
	s_cbranch_execz .LBB0_633
	v_add_f32_e32 v114, v114, v115
	v_add_f32_e32 v112, v112, v113
	v_add_f32_e32 v203, v203, v204
	v_add_f32_e32 v197, v197, v202
	v_add_f32_e32 v195, v195, v196
	v_add_f32_e32 v193, v193, v194
	v_add_f32_e32 v191, v191, v192
	v_add_f32_e32 v188, v188, v190
	ds_write2_b32 v189, v112, v114 offset1:8
	ds_write2_b32 v189, v188, v191 offset0:16 offset1:24
	ds_write2_b32 v189, v193, v195 offset0:128 offset1:136
	ds_write2_b32 v189, v197, v203 offset0:144 offset1:152
